# moba_attn: wave-uniform skip of non-own units whose 32 rows are all past cnt (nothing stored for them)
# speedup vs baseline: 1.0068x; 1.0068x over previous
.LBB0_1255:
	s_ashr_i32 s1, s0, 31
	s_lshl_b64 s[2:3], s[0:1], 2
	v_readlane_b32 s6, v253, 15
	v_readlane_b32 s7, v253, 16
	s_add_u32 s2, s6, s2
	s_addc_u32 s3, s7, s3
	s_lshl_b32 s2, s0, 1
	v_mov_b32_e32 v4, s2
	ds_read_u16 v4, v4 offset:1032
	s_cmp_eq_u32 s38, s4
	s_cselect_b64 s[42:43], -1, 0
	s_cmp_lg_u32 s38, s4
	s_cselect_b64 s[2:3], -1, 0
	s_not_b32 s4, s4
	s_add_i32 s4, s38, s4
	s_lshl_b32 s4, s4, 8
	s_lshl_b64 s[0:1], s[0:1], 13
	v_readlane_b32 s5, v253, 25
	s_add_u32 s0, s5, s0
	v_readlane_b32 s5, v253, 26
	s_addc_u32 s1, s5, s1
	s_mov_b64 s[6:7], -1
	s_and_b64 vcc, exec, s[2:3]
	s_cbranch_vccz .LBB0_1259
	v_add_u32_e32 v2, s4, v138
	s_waitcnt lgkmcnt(0)
	v_readfirstlane_b32 s8, v2
	v_readfirstlane_b32 s9, v4
	s_cmp_ge_i32 s8, s9
	s_cbranch_scc1 .LBB0_1248
	v_cmp_lt_i32_e32 vcc, v2, v4
	s_mov_b64 s[6:7], 0
	v_mov_b32_e32 v148, s19
	s_mov_b64 s[72:73], 0
	s_and_saveexec_b64 s[8:9], vcc
	s_cbranch_execz .LBB0_1258
	v_ashrrev_i32_e32 v3, 31, v2
	v_lshl_add_u64 v[2:3], v[2:3], 1, s[0:1]
	global_load_ushort v148, v[2:3], off
	s_mov_b64 s[72:73], exec
